# split-step GEMM loop (A halves + double-buffered B, LDS writes and global reloads interleaved with MFMAs) for ff1, ff2, w_out; W-phase prefetch for in-proj
# speedup vs baseline: 1.0246x; 1.0246x over previous
.LBB0_11:
	s_mul_hi_i32 s24, s26, 0x2e8ba2e9
	s_lshr_b32 s25, s24, 31
	s_ashr_i32 s24, s24, 1
	s_add_i32 s34, s24, s25
	s_mul_i32 s24, s34, -11
	s_abs_i32 s25, s34
	v_writelane_b32 v236, s26, 36
	s_add_i32 s5, s24, s26
	s_mul_hi_u32 s26, s25, s46
	s_mul_i32 s28, s26, s15
	s_ashr_i32 s35, s34, 31
	s_sub_i32 s25, s25, s28
	s_xor_b32 s24, s35, s14
	s_add_i32 s28, s26, 1
	s_sub_i32 s29, s25, s15
	s_cmp_ge_u32 s25, s15
	s_cselect_b32 s26, s28, s26
	s_cselect_b32 s25, s29, s25
	s_add_i32 s28, s26, 1
	s_cmp_ge_u32 s25, s15
	s_cselect_b32 s25, s28, s26
	s_xor_b32 s25, s25, s24
	s_sub_i32 s4, s25, s24
	s_mov_b32 s0, s4
	v_writelane_b32 v236, s0, 37
	v_readlane_b32 s36, v240, 14
	v_readlane_b32 s37, v240, 15
	v_writelane_b32 v236, s1, 38
	v_writelane_b32 v236, s34, 39
	s_mul_i32 s0, s4, s37
	s_mov_b64 s[24:25], -1
	v_writelane_b32 v236, s35, 40
	v_writelane_b32 v236, s0, 41
	s_sub_i32 s0, s34, s0
	v_writelane_b32 v236, s0, 43
	s_ashr_i32 s0, s0, 31
	v_writelane_b32 v236, s0, 45
	s_cmp_lt_i32 s5, 5
	v_readlane_b32 s38, v240, 16
	v_readlane_b32 s39, v240, 17
	v_writelane_b32 v236, s5, 47
	s_cbranch_scc1 .LBB0_139
	v_readlane_b32 s0, v236, 45
	s_mul_i32 s24, s16, s0
	v_readlane_b32 s0, v236, 43
	s_mul_hi_u32 s25, s16, s0
	s_add_i32 s24, s25, s24
	s_mul_i32 s25, s17, s0
	s_add_i32 s41, s24, s25
	s_mul_i32 s40, s16, s0
	v_readlane_b32 s0, v236, 47
	s_cmp_lt_i32 s0, 8
	s_mov_b64 s[24:25], -1
	s_cbranch_scc1 .LBB0_56
	v_readlane_b32 s0, v236, 47
	s_cmp_lt_i32 s0, 9
	s_cbranch_scc1 .LBB0_51
	v_readlane_b32 s0, v236, 47
	s_cmp_lt_i32 s0, 10
	s_cbranch_scc1 .LBB0_33
	v_readlane_b32 s0, v236, 47
	s_cmp_eq_u32 s0, 10
	s_cbranch_scc0 .LBB0_32
	s_waitcnt lgkmcnt(2)
	v_mov_b32_e32 v48, v184
	s_mov_b32 s24, s87
	s_and_b32 s25, s24, 7
	v_readlane_b32 s0, v236, 16
	s_mul_i32 s25, s25, s0
	s_ashr_i32 s24, s24, 3
	s_add_i32 s28, s25, s24
	s_cmp_ge_i32 s28, s18
	s_cbranch_scc1 .LBB0_32
	v_readlane_b32 s0, v236, 37
	s_lshl_b32 s24, s0, 23
	v_readlane_b32 s44, v239, 34
	v_readlane_b32 s1, v236, 38
	s_and_b32 s24, s24, 0x800000
	v_readlane_b32 s54, v239, 44
	v_readlane_b32 s55, v239, 45
	s_add_u32 s26, s54, s24
	v_readlane_b32 s0, v239, 18
	s_addc_u32 s33, s55, 0
	s_lshl_b64 s[24:25], s[40:41], 2
	v_readlane_b32 s4, v239, 22
	v_readlane_b32 s5, v239, 23
	s_add_u32 s24, s4, s24
	s_addc_u32 s25, s5, s25
	s_ashr_i32 s29, s28, 31
	s_lshr_b32 s29, s29, 26
	s_add_i32 s29, s28, s29
	s_ashr_i32 s34, s29, 6
	s_andn2_b32 s29, s29, 63
	s_sub_i32 s29, s28, s29
	s_lshl_b32 s35, s34, 3
	s_ashr_i32 s34, s29, 3
	s_and_b32 s29, s28, 7
	v_readlane_b32 s1, v239, 19
	v_readlane_b32 s2, v239, 20
	v_readlane_b32 s3, v239, 21
	v_readlane_b32 s6, v239, 24
	v_readlane_b32 s7, v239, 25
	v_readlane_b32 s8, v239, 26
	v_readlane_b32 s9, v239, 27
	v_readlane_b32 s10, v239, 28
	v_readlane_b32 s11, v239, 29
	v_readlane_b32 s12, v239, 30
	v_readlane_b32 s13, v239, 31
	v_readlane_b32 s14, v239, 32
	v_readlane_b32 s15, v239, 33
	s_or_b32 s36, s35, s29
	s_ashr_i32 s37, s36, 31
	v_readlane_b32 s0, v237, 30
	s_waitcnt vmcnt(17)
	v_mov_b32_e32 v4, v184
	s_lshl_b64 s[36:37], s[36:37], 21
	v_readlane_b32 s12, v237, 42
	v_readlane_b32 s13, v237, 43
	v_ashrrev_i32_e32 v0, 3, v4
	s_add_u32 s36, s12, s36
	v_ashrrev_i32_e32 v1, 31, v0
	s_addc_u32 s37, s13, s37
	v_lshlrev_b64 v[0:1], 13, v[0:1]
	v_lshlrev_b32_e32 v4, 4, v4
	v_lshl_add_u64 v[2:3], s[36:37], 0, v[0:1]
	v_and_b32_e32 v176, 0x70, v4
	s_mov_b32 s38, 0x40000
	s_waitcnt vmcnt(16)
	v_lshl_add_u64 v[28:29], v[2:3], 0, v[176:177]
	v_add_co_u32_e32 v4, vcc, s38, v28
	s_mov_b32 s29, 0x80000
	s_nop 0
	v_addc_co_u32_e32 v5, vcc, 0, v29, vcc
	v_add_co_u32_e32 v8, vcc, s29, v28
	s_mov_b32 s29, 0xc0000
	s_nop 0
	v_addc_co_u32_e32 v9, vcc, 0, v29, vcc
	v_add_co_u32_e32 v12, vcc, s29, v28
	s_mov_b32 s29, 0x100000
	s_nop 0
	v_addc_co_u32_e32 v13, vcc, 0, v29, vcc
	s_waitcnt lgkmcnt(0)
	v_add_co_u32_e32 v16, vcc, s29, v28
	s_ashr_i32 s35, s34, 31
	s_nop 0
	v_addc_co_u32_e32 v17, vcc, 0, v29, vcc
	s_mov_b32 s29, 0x140000
	s_lshl_b64 s[34:35], s[34:35], 20
	v_add_co_u32_e32 v20, vcc, s29, v28
	s_add_u32 s34, s26, s34
	s_nop 0
	v_addc_co_u32_e32 v21, vcc, 0, v29, vcc
	s_addc_u32 s35, s33, s35
	v_add_co_u32_e32 v24, vcc, 0x180000, v28
	v_lshl_add_u64 v[0:1], s[34:35], 0, v[0:1]
	s_nop 0
	v_addc_co_u32_e32 v25, vcc, 0, v29, vcc
	v_lshl_add_u64 v[44:45], v[0:1], 0, v[176:177]
	s_mov_b32 s100, 1
	global_load_dwordx4 v[0:3], v[28:29], off
	v_add_co_u32_e32 v28, vcc, 0x1c0000, v28
	global_load_dwordx4 v[4:7], v[4:5], off
	s_nop 0
	global_load_dwordx4 v[8:11], v[8:9], off
	v_addc_co_u32_e32 v29, vcc, 0, v29, vcc
	v_add_co_u32_e32 v36, vcc, s38, v44
	global_load_dwordx4 v[12:15], v[12:13], off
	s_nop 0
	global_load_dwordx4 v[16:19], v[16:17], off
	v_addc_co_u32_e32 v37, vcc, 0, v45, vcc
	v_add_co_u32_e32 v40, vcc, 0x80000, v44
	global_load_dwordx4 v[20:23], v[20:21], off
	s_nop 0
	global_load_dwordx4 v[24:27], v[24:25], off
	v_addc_co_u32_e32 v41, vcc, 0, v45, vcc
	global_load_dwordx4 v[28:31], v[28:29], off
	s_nop 0
	global_load_dwordx4 v[32:35], v[44:45], off
	v_add_co_u32_e32 v44, vcc, 0xc0000, v44
	global_load_dwordx4 v[36:39], v[36:37], off
	s_nop 0
	global_load_dwordx4 v[40:43], v[40:41], off
	v_addc_co_u32_e32 v45, vcc, 0, v45, vcc
	global_load_dwordx4 v[44:47], v[44:45], off
	s_waitcnt vmcnt(27)
	v_lshrrev_b32_e32 v49, 2, v48
	v_and_b32_e32 v49, 12, v49
	v_and_b32_e32 v179, 0xffffff8f, v48
	v_and_or_b32 v213, v48, 64, v49
	v_readlane_b32 s45, v239, 35
	v_readlane_b32 s46, v239, 36
	v_readlane_b32 s47, v239, 37
	v_readlane_b32 s48, v239, 38
	v_readlane_b32 s49, v239, 39
	v_readlane_b32 s50, v239, 40
	v_readlane_b32 s51, v239, 41
	v_readlane_b32 s52, v239, 42
	v_readlane_b32 s53, v239, 43
	v_readlane_b32 s56, v239, 46
	v_readlane_b32 s57, v239, 47
	v_readlane_b32 s58, v239, 48
	v_readlane_b32 s59, v239, 49
	v_readlane_b32 s1, v237, 31
	v_readlane_b32 s2, v237, 32
	v_readlane_b32 s3, v237, 33
	v_readlane_b32 s4, v237, 34
	v_readlane_b32 s5, v237, 35
	v_readlane_b32 s6, v237, 36
	v_readlane_b32 s7, v237, 37
	v_readlane_b32 s8, v237, 38
	v_readlane_b32 s9, v237, 39
	v_readlane_b32 s10, v237, 40
	v_readlane_b32 s11, v237, 41
	v_readlane_b32 s14, v237, 44
	v_readlane_b32 s15, v237, 45
	s_branch .LBB0_19

.LBB0_23:
	s_cmpk_gt_u32 s45, 0xfbf
	s_cselect_b64 s[28:29], -1, 0
	s_cmp_lg_u32 s45, 0
	s_cbranch_scc1 .Ls_nosetup_ff2
	v_add_u32_e32 v176, v182, v180
	v_add_u32_e32 v243, v182, v183
	v_add_u32_e32 v241, v181, v180
	v_add_u32_e32 v242, v181, v183
	v_or_b32_e32 v215, 0x4000, v214
	v_lshrrev_b32_e32 v180, 3, v184
	v_and_b32_e32 v181, 7, v184
	v_lshlrev_b32_e32 v180, 13, v180
	v_lshl_add_u32 v180, v181, 4, v180
	s_cmp_eq_u32 s100, 0
	s_cbranch_scc1 .Ls_nosetup_ff2
	s_mov_b32 s100, 0
	s_waitcnt vmcnt(0)
	ds_write_b128 v214, v[0:3]
	ds_write_b128 v214, v[4:7] offset:4096
	ds_write_b128 v214, v[16:19] offset:16384
	ds_write_b128 v214, v[20:23] offset:20480
	ds_write_b128 v214, v[32:35] offset:32768
	ds_write_b128 v214, v[36:39] offset:36864
	ds_write_b128 v214, v[40:43] offset:40960
	ds_write_b128 v214, v[44:47] offset:45056
	s_add_u32 s86, s50, 128
	s_addc_u32 s87, s51, 0
	s_add_u32 s34, s92, 128
	s_addc_u32 s35, s93, 0
	global_load_dwordx4 v[32:35], v180, s[34:35]
	s_add_u32 s98, s34, 0x40000
	s_addc_u32 s99, s35, 0
	global_load_dwordx4 v[36:39], v180, s[98:99]
	global_load_dwordx4 v[0:3], v180, s[86:87]
	s_add_u32 s98, s86, 0x40000
	s_addc_u32 s99, s87, 0
	global_load_dwordx4 v[4:7], v180, s[98:99]
	s_add_u32 s98, s86, 0x100000
	s_addc_u32 s99, s87, 0
	global_load_dwordx4 v[16:19], v180, s[98:99]
	s_add_u32 s98, s86, 0x140000
	s_addc_u32 s99, s87, 0
	global_load_dwordx4 v[20:23], v180, s[98:99]
	s_add_u32 s98, s34, 0x80000
	s_addc_u32 s99, s35, 0
	global_load_dwordx4 v[40:43], v180, s[98:99]
	s_add_u32 s98, s34, 0xc0000
	s_addc_u32 s99, s35, 0
	global_load_dwordx4 v[44:47], v180, s[98:99]
	s_waitcnt lgkmcnt(0)
	s_barrier
.Ls_nosetup_ff2:
	s_add_i32 s101, s45, 64
	s_cmpk_ge_u32 s101, 0x1000
	s_cselect_b32 s98, 0x1000, 0
	s_cselect_b32 s99, s94, 0
	s_sub_u32 s101, s101, s98
	s_lshl_b32 s101, s101, 1
	s_cmp_lg_u32 s99, 0
	s_cselect_b64 s[84:85], s[38:39], s[50:51]
	s_add_u32 s84, s84, s101
	s_addc_u32 s85, s85, 0
	s_add_i32 s101, s45, 128
	s_cmpk_ge_u32 s101, 0x1000
	s_cselect_b32 s98, 0x1000, 0
	s_cselect_b32 s99, s94, 0
	s_sub_u32 s101, s101, s98
	s_lshl_b32 s101, s101, 1
	s_cmp_lg_u32 s99, 0
	s_cselect_b64 s[86:87], s[38:39], s[50:51]
	s_cselect_b64 s[34:35], s[42:43], s[92:93]
	s_add_u32 s86, s86, s101
	s_addc_u32 s87, s87, 0
	s_add_u32 s34, s34, s101
	s_addc_u32 s35, s35, 0
	ds_read_b128 v[216:219], v176 offset:32768
	ds_read_b128 v[232:235], v241
	ds_read_b128 v[220:223], v176 offset:34816
	ds_read_b128 v[224:227], v176 offset:36864
	ds_read_b128 v[228:231], v176 offset:38912
	ds_read_b128 v[244:247], v241 offset:2048
	ds_read_b128 v[248:251], v241 offset:4096
	ds_read_b128 v[252:255], v241 offset:6144
	s_waitcnt lgkmcnt(6)
	v_mfma_f32_16x16x32_bf16 v[172:175], v[216:219], v[232:235], v[172:175]
	s_waitcnt lgkmcnt(5)
	v_mfma_f32_16x16x32_bf16 v[168:171], v[220:223], v[232:235], v[168:171]
	s_waitcnt lgkmcnt(4)
	v_mfma_f32_16x16x32_bf16 v[164:167], v[224:227], v[232:235], v[164:167]
	s_waitcnt lgkmcnt(3)
	v_mfma_f32_16x16x32_bf16 v[160:163], v[228:231], v[232:235], v[160:163]
	ds_read_b128 v[232:235], v242
	s_waitcnt vmcnt(11)
	ds_write_b128 v214, v[8:11] offset:8192
	s_add_u32 s98, s84, 0x80000
	s_addc_u32 s99, s85, 0
	global_load_dwordx4 v[8:11], v180, s[98:99]
	s_waitcnt lgkmcnt(4)
	v_mfma_f32_16x16x32_bf16 v[156:159], v[216:219], v[244:247], v[156:159]
	v_mfma_f32_16x16x32_bf16 v[152:155], v[220:223], v[244:247], v[152:155]
	v_mfma_f32_16x16x32_bf16 v[148:151], v[224:227], v[244:247], v[148:151]
	v_mfma_f32_16x16x32_bf16 v[144:147], v[228:231], v[244:247], v[144:147]
	ds_read_b128 v[244:247], v242 offset:2048
	s_waitcnt vmcnt(11)
	ds_write_b128 v214, v[12:15] offset:12288
	s_add_u32 s98, s84, 0xc0000
	s_addc_u32 s99, s85, 0
	global_load_dwordx4 v[12:15], v180, s[98:99]
	s_waitcnt lgkmcnt(5)
	v_mfma_f32_16x16x32_bf16 v[140:143], v[216:219], v[248:251], v[140:143]
	s_waitcnt lgkmcnt(4)
	v_mfma_f32_16x16x32_bf16 v[124:127], v[216:219], v[252:255], v[124:127]
	ds_read_b128 v[216:219], v243 offset:32768
	v_mfma_f32_16x16x32_bf16 v[136:139], v[220:223], v[248:251], v[136:139]
	v_mfma_f32_16x16x32_bf16 v[120:123], v[220:223], v[252:255], v[120:123]
	ds_read_b128 v[220:223], v243 offset:34816
	v_mfma_f32_16x16x32_bf16 v[132:135], v[224:227], v[248:251], v[132:135]
	v_mfma_f32_16x16x32_bf16 v[116:119], v[224:227], v[252:255], v[116:119]
	ds_read_b128 v[224:227], v243 offset:36864
	v_mfma_f32_16x16x32_bf16 v[128:131], v[228:231], v[248:251], v[128:131]
	v_mfma_f32_16x16x32_bf16 v[112:115], v[228:231], v[252:255], v[112:115]
	ds_read_b128 v[228:231], v243 offset:38912
	ds_read_b128 v[248:251], v242 offset:4096
	ds_read_b128 v[252:255], v242 offset:6144
	s_waitcnt vmcnt(11)
	ds_write_b128 v214, v[24:27] offset:24576
	s_add_u32 s98, s84, 0x180000
	s_addc_u32 s99, s85, 0
	global_load_dwordx4 v[24:27], v180, s[98:99]
	s_waitcnt lgkmcnt(6)
	v_mfma_f32_16x16x32_bf16 v[172:175], v[216:219], v[232:235], v[172:175]
	v_mfma_f32_16x16x32_bf16 v[156:159], v[216:219], v[244:247], v[156:159]
	s_waitcnt lgkmcnt(5)
	v_mfma_f32_16x16x32_bf16 v[168:171], v[220:223], v[232:235], v[168:171]
	v_mfma_f32_16x16x32_bf16 v[152:155], v[220:223], v[244:247], v[152:155]
	s_waitcnt vmcnt(11)
	ds_write_b128 v214, v[28:31] offset:28672
	s_add_u32 s98, s84, 0x1c0000
	s_addc_u32 s99, s85, 0
	global_load_dwordx4 v[28:31], v180, s[98:99]
	s_waitcnt lgkmcnt(5)
	v_mfma_f32_16x16x32_bf16 v[164:167], v[224:227], v[232:235], v[164:167]
	v_mfma_f32_16x16x32_bf16 v[148:151], v[224:227], v[244:247], v[148:151]
	s_waitcnt lgkmcnt(4)
	v_mfma_f32_16x16x32_bf16 v[160:163], v[228:231], v[232:235], v[160:163]
	v_mfma_f32_16x16x32_bf16 v[144:147], v[228:231], v[244:247], v[144:147]
	s_waitcnt vmcnt(11)
	ds_write_b128 v215, v[32:35] offset:32768
	global_load_dwordx4 v[32:35], v180, s[34:35]
	s_waitcnt lgkmcnt(4)
	v_mfma_f32_16x16x32_bf16 v[140:143], v[216:219], v[248:251], v[140:143]
	v_mfma_f32_16x16x32_bf16 v[136:139], v[220:223], v[248:251], v[136:139]
	v_mfma_f32_16x16x32_bf16 v[132:135], v[224:227], v[248:251], v[132:135]
	v_mfma_f32_16x16x32_bf16 v[128:131], v[228:231], v[248:251], v[128:131]
	s_waitcnt vmcnt(11)
	ds_write_b128 v215, v[36:39] offset:36864
	s_add_u32 s98, s34, 0x40000
	s_addc_u32 s99, s35, 0
	global_load_dwordx4 v[36:39], v180, s[98:99]
	s_waitcnt lgkmcnt(0)
	s_barrier
	v_mfma_f32_16x16x32_bf16 v[124:127], v[216:219], v[252:255], v[124:127]
	v_mfma_f32_16x16x32_bf16 v[120:123], v[220:223], v[252:255], v[120:123]
	v_mfma_f32_16x16x32_bf16 v[116:119], v[224:227], v[252:255], v[116:119]
	v_mfma_f32_16x16x32_bf16 v[112:115], v[228:231], v[252:255], v[112:115]
	ds_read_b128 v[216:219], v176 offset:32768
	ds_read_b128 v[232:235], v241 offset:8192
	ds_read_b128 v[220:223], v176 offset:34816
	ds_read_b128 v[224:227], v176 offset:36864
	ds_read_b128 v[228:231], v176 offset:38912
	ds_read_b128 v[244:247], v241 offset:10240
	ds_read_b128 v[248:251], v241 offset:12288
	ds_read_b128 v[252:255], v241 offset:14336
	s_waitcnt lgkmcnt(6)
	v_mfma_f32_16x16x32_bf16 v[108:111], v[216:219], v[232:235], v[108:111]
	s_waitcnt lgkmcnt(5)
	v_mfma_f32_16x16x32_bf16 v[104:107], v[220:223], v[232:235], v[104:107]
	s_waitcnt lgkmcnt(4)
	v_mfma_f32_16x16x32_bf16 v[100:103], v[224:227], v[232:235], v[100:103]
	s_waitcnt lgkmcnt(3)
	v_mfma_f32_16x16x32_bf16 v[96:99], v[228:231], v[232:235], v[96:99]
	ds_read_b128 v[232:235], v242 offset:8192
	s_waitcnt vmcnt(11)
	ds_write_b128 v214, v[0:3]
	global_load_dwordx4 v[0:3], v180, s[86:87]
	s_waitcnt lgkmcnt(4)
	v_mfma_f32_16x16x32_bf16 v[92:95], v[216:219], v[244:247], v[92:95]
	v_mfma_f32_16x16x32_bf16 v[88:91], v[220:223], v[244:247], v[88:91]
	v_mfma_f32_16x16x32_bf16 v[84:87], v[224:227], v[244:247], v[84:87]
	v_mfma_f32_16x16x32_bf16 v[80:83], v[228:231], v[244:247], v[80:83]
	ds_read_b128 v[244:247], v242 offset:10240
	s_waitcnt vmcnt(11)
	ds_write_b128 v214, v[4:7] offset:4096
	s_add_u32 s98, s86, 0x40000
	s_addc_u32 s99, s87, 0
	global_load_dwordx4 v[4:7], v180, s[98:99]
	s_waitcnt lgkmcnt(5)
	v_mfma_f32_16x16x32_bf16 v[76:79], v[216:219], v[248:251], v[76:79]
	s_waitcnt lgkmcnt(4)
	v_mfma_f32_16x16x32_bf16 v[60:63], v[216:219], v[252:255], v[60:63]
	ds_read_b128 v[216:219], v243 offset:32768
	v_mfma_f32_16x16x32_bf16 v[72:75], v[220:223], v[248:251], v[72:75]
	v_mfma_f32_16x16x32_bf16 v[56:59], v[220:223], v[252:255], v[56:59]
	ds_read_b128 v[220:223], v243 offset:34816
	v_mfma_f32_16x16x32_bf16 v[68:71], v[224:227], v[248:251], v[68:71]
	v_mfma_f32_16x16x32_bf16 v[52:55], v[224:227], v[252:255], v[52:55]
	ds_read_b128 v[224:227], v243 offset:36864
	v_mfma_f32_16x16x32_bf16 v[64:67], v[228:231], v[248:251], v[64:67]
	v_mfma_f32_16x16x32_bf16 v[48:51], v[228:231], v[252:255], v[48:51]
	ds_read_b128 v[228:231], v243 offset:38912
	ds_read_b128 v[248:251], v242 offset:12288
	ds_read_b128 v[252:255], v242 offset:14336
	s_waitcnt vmcnt(11)
	ds_write_b128 v214, v[16:19] offset:16384
	s_add_u32 s98, s86, 0x100000
	s_addc_u32 s99, s87, 0
	global_load_dwordx4 v[16:19], v180, s[98:99]
	s_waitcnt lgkmcnt(6)
	v_mfma_f32_16x16x32_bf16 v[108:111], v[216:219], v[232:235], v[108:111]
	v_mfma_f32_16x16x32_bf16 v[92:95], v[216:219], v[244:247], v[92:95]
	s_waitcnt lgkmcnt(5)
	v_mfma_f32_16x16x32_bf16 v[104:107], v[220:223], v[232:235], v[104:107]
	v_mfma_f32_16x16x32_bf16 v[88:91], v[220:223], v[244:247], v[88:91]
	s_waitcnt vmcnt(11)
	ds_write_b128 v214, v[20:23] offset:20480
	s_add_u32 s98, s86, 0x140000
	s_addc_u32 s99, s87, 0
	global_load_dwordx4 v[20:23], v180, s[98:99]
	s_waitcnt lgkmcnt(5)
	v_mfma_f32_16x16x32_bf16 v[100:103], v[224:227], v[232:235], v[100:103]
	v_mfma_f32_16x16x32_bf16 v[84:87], v[224:227], v[244:247], v[84:87]
	s_waitcnt lgkmcnt(4)
	v_mfma_f32_16x16x32_bf16 v[96:99], v[228:231], v[232:235], v[96:99]
	v_mfma_f32_16x16x32_bf16 v[80:83], v[228:231], v[244:247], v[80:83]
	s_waitcnt vmcnt(11)
	ds_write_b128 v215, v[40:43] offset:40960
	s_add_u32 s98, s34, 0x80000
	s_addc_u32 s99, s35, 0
	global_load_dwordx4 v[40:43], v180, s[98:99]
	s_waitcnt lgkmcnt(4)
	v_mfma_f32_16x16x32_bf16 v[76:79], v[216:219], v[248:251], v[76:79]
	v_mfma_f32_16x16x32_bf16 v[72:75], v[220:223], v[248:251], v[72:75]
	v_mfma_f32_16x16x32_bf16 v[68:71], v[224:227], v[248:251], v[68:71]
	v_mfma_f32_16x16x32_bf16 v[64:67], v[228:231], v[248:251], v[64:67]
	s_waitcnt vmcnt(11)
	ds_write_b128 v215, v[44:47] offset:45056
	s_add_u32 s98, s34, 0xc0000
	s_addc_u32 s99, s35, 0
	global_load_dwordx4 v[44:47], v180, s[98:99]
	s_waitcnt lgkmcnt(0)
	s_barrier
	v_mfma_f32_16x16x32_bf16 v[60:63], v[216:219], v[252:255], v[60:63]
	v_mfma_f32_16x16x32_bf16 v[56:59], v[220:223], v[252:255], v[56:59]
	v_mfma_f32_16x16x32_bf16 v[52:55], v[224:227], v[252:255], v[52:55]
	v_mfma_f32_16x16x32_bf16 v[48:51], v[228:231], v[252:255], v[48:51]
	v_xor_b32_e32 v176, 0x4000, v176
	v_xor_b32_e32 v243, 0x4000, v243
	v_xor_b32_e32 v215, 0x4000, v215
	s_and_b32 s98, s28, s94
	s_cmp_lg_u32 s98, s28
	s_cbranch_scc0 .Ls_nodrain_ff2
	s_waitcnt vmcnt(0)
.Ls_nodrain_ff2:
	s_add_i32 s45, s45, 64
	s_andn2_b64 vcc, exec, s[28:29]
	s_mov_b32 s85, 0x800000
	s_cbranch_vccz .LBB0_18
	s_branch .LBB0_23

.LBB0_33:
	s_andn2_b64 vcc, exec, s[24:25]
	s_cbranch_vccnz .LBB0_50
	s_waitcnt lgkmcnt(2)
	v_mov_b32_e32 v48, v184
	s_mov_b32 s24, s87
	s_and_b32 s25, s24, 7
	v_readlane_b32 s0, v236, 16
	s_mul_i32 s25, s25, s0
	s_ashr_i32 s24, s24, 3
	s_add_i32 s28, s25, s24
	v_readlane_b32 s0, v239, 50
	s_cmp_ge_i32 s28, s0
	s_cbranch_scc1 .LBB0_50
	s_ashr_i32 s24, s28, 31
	s_lshr_b32 s24, s24, 24
	s_add_i32 s24, s28, s24
	s_ashr_i32 s25, s24, 8
	s_lshl_b32 s25, s25, 3
	s_and_b32 s26, s28, 7
	s_and_b32 s24, s24, 0xffffff00
	s_or_b32 s34, s25, s26
	s_sub_i32 s24, s28, s24
	s_ashr_i32 s35, s34, 31
	s_waitcnt vmcnt(17)
	v_mov_b32_e32 v4, v184
	s_ashr_i32 s24, s24, 3
	s_lshl_b64 s[34:35], s[34:35], 19
	s_add_u32 s34, s76, s34
	v_ashrrev_i32_e32 v0, 3, v4
	v_ashrrev_i32_e32 v1, 31, v0
	s_addc_u32 s35, s77, s35
	v_lshlrev_b64 v[0:1], 11, v[0:1]
	v_lshlrev_b32_e32 v4, 4, v4
	v_lshl_add_u64 v[2:3], s[34:35], 0, v[0:1]
	v_and_b32_e32 v176, 0x70, v4
	s_mov_b32 s1, 0x10000
	s_waitcnt vmcnt(16)
	v_lshl_add_u64 v[28:29], v[2:3], 0, v[176:177]
	v_add_co_u32_e32 v4, vcc, s1, v28
	s_mov_b32 s2, 0x20000
	s_nop 0
	v_addc_co_u32_e32 v5, vcc, 0, v29, vcc
	v_add_co_u32_e32 v8, vcc, s2, v28
	s_mov_b32 s3, 0x30000
	s_nop 0
	v_addc_co_u32_e32 v9, vcc, 0, v29, vcc
	v_add_co_u32_e32 v12, vcc, s3, v28
	s_mov_b32 s0, 0x40000
	s_nop 0
	v_addc_co_u32_e32 v13, vcc, 0, v29, vcc
	s_waitcnt lgkmcnt(0)
	v_add_co_u32_e32 v16, vcc, s0, v28
	s_ashr_i32 s25, s24, 31
	v_readlane_b32 s44, v239, 34
	v_addc_co_u32_e32 v17, vcc, 0, v29, vcc
	s_mov_b32 s0, 0x50000
	s_lshl_b64 s[24:25], s[24:25], 18
	v_readlane_b32 s52, v239, 42
	v_add_co_u32_e32 v20, vcc, s0, v28
	v_readlane_b32 s53, v239, 43
	s_add_u32 s24, s52, s24
	v_addc_co_u32_e32 v21, vcc, 0, v29, vcc
	s_addc_u32 s25, s53, s25
	v_add_co_u32_e32 v24, vcc, 0x60000, v28
	v_lshl_add_u64 v[0:1], s[24:25], 0, v[0:1]
	s_nop 0
	v_addc_co_u32_e32 v25, vcc, 0, v29, vcc
	v_lshl_add_u64 v[44:45], v[0:1], 0, v[176:177]
	s_mov_b32 s100, 1
	global_load_dwordx4 v[0:3], v[28:29], off
	v_add_co_u32_e32 v28, vcc, 0x70000, v28
	global_load_dwordx4 v[4:7], v[4:5], off
	s_nop 0
	global_load_dwordx4 v[8:11], v[8:9], off
	v_addc_co_u32_e32 v29, vcc, 0, v29, vcc
	v_add_co_u32_e32 v36, vcc, s1, v44
	global_load_dwordx4 v[12:15], v[12:13], off
	s_nop 0
	global_load_dwordx4 v[16:19], v[16:17], off
	v_addc_co_u32_e32 v37, vcc, 0, v45, vcc
	v_add_co_u32_e32 v40, vcc, 0x20000, v44
	global_load_dwordx4 v[20:23], v[20:21], off
	s_nop 0
	global_load_dwordx4 v[24:27], v[24:25], off
	v_addc_co_u32_e32 v41, vcc, 0, v45, vcc
	global_load_dwordx4 v[28:31], v[28:29], off
	s_nop 0
	global_load_dwordx4 v[32:35], v[44:45], off
	v_add_co_u32_e32 v44, vcc, 0x30000, v44
	global_load_dwordx4 v[36:39], v[36:37], off
	s_nop 0
	global_load_dwordx4 v[40:43], v[40:41], off
	v_addc_co_u32_e32 v45, vcc, 0, v45, vcc
	global_load_dwordx4 v[44:47], v[44:45], off
	s_waitcnt vmcnt(27)
	v_lshrrev_b32_e32 v49, 2, v48
	v_and_b32_e32 v49, 12, v49
	v_and_b32_e32 v179, 0xffffff8f, v48
	v_and_or_b32 v182, v48, 64, v49
	v_readlane_b32 s45, v239, 35
	v_readlane_b32 s46, v239, 36
	v_readlane_b32 s47, v239, 37
	v_readlane_b32 s48, v239, 38
	v_readlane_b32 s49, v239, 39
	v_readlane_b32 s50, v239, 40
	v_readlane_b32 s51, v239, 41
	v_readlane_b32 s54, v239, 44
	v_readlane_b32 s55, v239, 45
	v_readlane_b32 s56, v239, 46
	v_readlane_b32 s57, v239, 47
	v_readlane_b32 s58, v239, 48
	v_readlane_b32 s59, v239, 49
	s_branch .LBB0_37

.LBB0_41:
	s_cmpk_gt_u32 s33, 0x3bf
	s_cselect_b64 s[28:29], -1, 0
	s_cmp_lg_u32 s33, 0
	s_cbranch_scc1 .Ls_nosetup_ff1
	v_add_u32_e32 v176, v183, v180
	v_add_u32_e32 v243, v183, v213
	v_add_u32_e32 v241, v181, v180
	v_add_u32_e32 v242, v181, v213
	v_or_b32_e32 v215, 0x4000, v214
	v_lshrrev_b32_e32 v180, 3, v184
	v_and_b32_e32 v181, 7, v184
	v_lshlrev_b32_e32 v180, 11, v180
	v_lshl_add_u32 v180, v181, 4, v180
	s_cmp_eq_u32 s100, 0
	s_cbranch_scc1 .Ls_nosetup_ff1
	s_mov_b32 s100, 0
	s_waitcnt vmcnt(0)
	ds_write_b128 v214, v[0:3]
	ds_write_b128 v214, v[4:7] offset:4096
	ds_write_b128 v214, v[16:19] offset:16384
	ds_write_b128 v214, v[20:23] offset:20480
	ds_write_b128 v214, v[32:35] offset:32768
	ds_write_b128 v214, v[36:39] offset:36864
	ds_write_b128 v214, v[40:43] offset:40960
	ds_write_b128 v214, v[44:47] offset:45056
	s_add_u32 s86, s46, 128
	s_addc_u32 s87, s47, 0
	s_add_u32 s34, s50, 128
	s_addc_u32 s35, s51, 0
	global_load_dwordx4 v[32:35], v180, s[34:35]
	s_add_u32 s98, s34, 0x10000
	s_addc_u32 s99, s35, 0
	global_load_dwordx4 v[36:39], v180, s[98:99]
	global_load_dwordx4 v[0:3], v180, s[86:87]
	s_add_u32 s98, s86, 0x10000
	s_addc_u32 s99, s87, 0
	global_load_dwordx4 v[4:7], v180, s[98:99]
	s_add_u32 s98, s86, 0x40000
	s_addc_u32 s99, s87, 0
	global_load_dwordx4 v[16:19], v180, s[98:99]
	s_add_u32 s98, s86, 0x50000
	s_addc_u32 s99, s87, 0
	global_load_dwordx4 v[20:23], v180, s[98:99]
	s_add_u32 s98, s34, 0x20000
	s_addc_u32 s99, s35, 0
	global_load_dwordx4 v[40:43], v180, s[98:99]
	s_add_u32 s98, s34, 0x30000
	s_addc_u32 s99, s35, 0
	global_load_dwordx4 v[44:47], v180, s[98:99]
	s_waitcnt lgkmcnt(0)
	s_barrier
.Ls_nosetup_ff1:
	s_add_i32 s101, s33, 64
	s_cmpk_ge_u32 s101, 0x400
	s_cselect_b32 s98, 0x400, 0
	s_cselect_b32 s99, s92, 0
	s_sub_u32 s101, s101, s98
	s_lshl_b32 s101, s101, 1
	s_cmp_lg_u32 s99, 0
	s_cselect_b64 s[84:85], s[36:37], s[46:47]
	s_add_u32 s84, s84, s101
	s_addc_u32 s85, s85, 0
	s_add_i32 s101, s33, 128
	s_cmpk_ge_u32 s101, 0x400
	s_cselect_b32 s98, 0x400, 0
	s_cselect_b32 s99, s92, 0
	s_sub_u32 s101, s101, s98
	s_lshl_b32 s101, s101, 1
	s_cmp_lg_u32 s99, 0
	s_cselect_b64 s[86:87], s[36:37], s[46:47]
	s_cselect_b64 s[34:35], s[38:39], s[50:51]
	s_add_u32 s86, s86, s101
	s_addc_u32 s87, s87, 0
	s_add_u32 s34, s34, s101
	s_addc_u32 s35, s35, 0
	ds_read_b128 v[216:219], v176 offset:32768
	ds_read_b128 v[232:235], v241
	ds_read_b128 v[220:223], v176 offset:34816
	ds_read_b128 v[224:227], v176 offset:36864
	ds_read_b128 v[228:231], v176 offset:38912
	ds_read_b128 v[244:247], v241 offset:2048
	ds_read_b128 v[248:251], v241 offset:4096
	ds_read_b128 v[252:255], v241 offset:6144
	s_waitcnt lgkmcnt(6)
	v_mfma_f32_16x16x32_bf16 v[172:175], v[216:219], v[232:235], v[172:175]
	s_waitcnt lgkmcnt(5)
	v_mfma_f32_16x16x32_bf16 v[168:171], v[220:223], v[232:235], v[168:171]
	s_waitcnt lgkmcnt(4)
	v_mfma_f32_16x16x32_bf16 v[164:167], v[224:227], v[232:235], v[164:167]
	s_waitcnt lgkmcnt(3)
	v_mfma_f32_16x16x32_bf16 v[160:163], v[228:231], v[232:235], v[160:163]
	ds_read_b128 v[232:235], v242
	s_waitcnt vmcnt(11)
	ds_write_b128 v214, v[8:11] offset:8192
	s_add_u32 s98, s84, 0x20000
	s_addc_u32 s99, s85, 0
	global_load_dwordx4 v[8:11], v180, s[98:99]
	s_waitcnt lgkmcnt(4)
	v_mfma_f32_16x16x32_bf16 v[156:159], v[216:219], v[244:247], v[156:159]
	v_mfma_f32_16x16x32_bf16 v[152:155], v[220:223], v[244:247], v[152:155]
	v_mfma_f32_16x16x32_bf16 v[148:151], v[224:227], v[244:247], v[148:151]
	v_mfma_f32_16x16x32_bf16 v[144:147], v[228:231], v[244:247], v[144:147]
	ds_read_b128 v[244:247], v242 offset:2048
	s_waitcnt vmcnt(11)
	ds_write_b128 v214, v[12:15] offset:12288
	s_add_u32 s98, s84, 0x30000
	s_addc_u32 s99, s85, 0
	global_load_dwordx4 v[12:15], v180, s[98:99]
	s_waitcnt lgkmcnt(5)
	v_mfma_f32_16x16x32_bf16 v[140:143], v[216:219], v[248:251], v[140:143]
	s_waitcnt lgkmcnt(4)
	v_mfma_f32_16x16x32_bf16 v[124:127], v[216:219], v[252:255], v[124:127]
	ds_read_b128 v[216:219], v243 offset:32768
	v_mfma_f32_16x16x32_bf16 v[136:139], v[220:223], v[248:251], v[136:139]
	v_mfma_f32_16x16x32_bf16 v[120:123], v[220:223], v[252:255], v[120:123]
	ds_read_b128 v[220:223], v243 offset:34816
	v_mfma_f32_16x16x32_bf16 v[132:135], v[224:227], v[248:251], v[132:135]
	v_mfma_f32_16x16x32_bf16 v[116:119], v[224:227], v[252:255], v[116:119]
	ds_read_b128 v[224:227], v243 offset:36864
	v_mfma_f32_16x16x32_bf16 v[128:131], v[228:231], v[248:251], v[128:131]
	v_mfma_f32_16x16x32_bf16 v[112:115], v[228:231], v[252:255], v[112:115]
	ds_read_b128 v[228:231], v243 offset:38912
	ds_read_b128 v[248:251], v242 offset:4096
	ds_read_b128 v[252:255], v242 offset:6144
	s_waitcnt vmcnt(11)
	ds_write_b128 v214, v[24:27] offset:24576
	s_add_u32 s98, s84, 0x60000
	s_addc_u32 s99, s85, 0
	global_load_dwordx4 v[24:27], v180, s[98:99]
	s_waitcnt lgkmcnt(6)
	v_mfma_f32_16x16x32_bf16 v[172:175], v[216:219], v[232:235], v[172:175]
	v_mfma_f32_16x16x32_bf16 v[156:159], v[216:219], v[244:247], v[156:159]
	s_waitcnt lgkmcnt(5)
	v_mfma_f32_16x16x32_bf16 v[168:171], v[220:223], v[232:235], v[168:171]
	v_mfma_f32_16x16x32_bf16 v[152:155], v[220:223], v[244:247], v[152:155]
	s_waitcnt vmcnt(11)
	ds_write_b128 v214, v[28:31] offset:28672
	s_add_u32 s98, s84, 0x70000
	s_addc_u32 s99, s85, 0
	global_load_dwordx4 v[28:31], v180, s[98:99]
	s_waitcnt lgkmcnt(5)
	v_mfma_f32_16x16x32_bf16 v[164:167], v[224:227], v[232:235], v[164:167]
	v_mfma_f32_16x16x32_bf16 v[148:151], v[224:227], v[244:247], v[148:151]
	s_waitcnt lgkmcnt(4)
	v_mfma_f32_16x16x32_bf16 v[160:163], v[228:231], v[232:235], v[160:163]
	v_mfma_f32_16x16x32_bf16 v[144:147], v[228:231], v[244:247], v[144:147]
	s_waitcnt vmcnt(11)
	ds_write_b128 v215, v[32:35] offset:32768
	global_load_dwordx4 v[32:35], v180, s[34:35]
	s_waitcnt lgkmcnt(4)
	v_mfma_f32_16x16x32_bf16 v[140:143], v[216:219], v[248:251], v[140:143]
	v_mfma_f32_16x16x32_bf16 v[136:139], v[220:223], v[248:251], v[136:139]
	v_mfma_f32_16x16x32_bf16 v[132:135], v[224:227], v[248:251], v[132:135]
	v_mfma_f32_16x16x32_bf16 v[128:131], v[228:231], v[248:251], v[128:131]
	s_waitcnt vmcnt(11)
	ds_write_b128 v215, v[36:39] offset:36864
	s_add_u32 s98, s34, 0x10000
	s_addc_u32 s99, s35, 0
	global_load_dwordx4 v[36:39], v180, s[98:99]
	s_waitcnt lgkmcnt(0)
	s_barrier
	v_mfma_f32_16x16x32_bf16 v[124:127], v[216:219], v[252:255], v[124:127]
	v_mfma_f32_16x16x32_bf16 v[120:123], v[220:223], v[252:255], v[120:123]
	v_mfma_f32_16x16x32_bf16 v[116:119], v[224:227], v[252:255], v[116:119]
	v_mfma_f32_16x16x32_bf16 v[112:115], v[228:231], v[252:255], v[112:115]
	ds_read_b128 v[216:219], v176 offset:32768
	ds_read_b128 v[232:235], v241 offset:8192
	ds_read_b128 v[220:223], v176 offset:34816
	ds_read_b128 v[224:227], v176 offset:36864
	ds_read_b128 v[228:231], v176 offset:38912
	ds_read_b128 v[244:247], v241 offset:10240
	ds_read_b128 v[248:251], v241 offset:12288
	ds_read_b128 v[252:255], v241 offset:14336
	s_waitcnt lgkmcnt(6)
	v_mfma_f32_16x16x32_bf16 v[108:111], v[216:219], v[232:235], v[108:111]
	s_waitcnt lgkmcnt(5)
	v_mfma_f32_16x16x32_bf16 v[104:107], v[220:223], v[232:235], v[104:107]
	s_waitcnt lgkmcnt(4)
	v_mfma_f32_16x16x32_bf16 v[100:103], v[224:227], v[232:235], v[100:103]
	s_waitcnt lgkmcnt(3)
	v_mfma_f32_16x16x32_bf16 v[96:99], v[228:231], v[232:235], v[96:99]
	ds_read_b128 v[232:235], v242 offset:8192
	s_waitcnt vmcnt(11)
	ds_write_b128 v214, v[0:3]
	global_load_dwordx4 v[0:3], v180, s[86:87]
	s_waitcnt lgkmcnt(4)
	v_mfma_f32_16x16x32_bf16 v[92:95], v[216:219], v[244:247], v[92:95]
	v_mfma_f32_16x16x32_bf16 v[88:91], v[220:223], v[244:247], v[88:91]
	v_mfma_f32_16x16x32_bf16 v[84:87], v[224:227], v[244:247], v[84:87]
	v_mfma_f32_16x16x32_bf16 v[80:83], v[228:231], v[244:247], v[80:83]
	ds_read_b128 v[244:247], v242 offset:10240
	s_waitcnt vmcnt(11)
	ds_write_b128 v214, v[4:7] offset:4096
	s_add_u32 s98, s86, 0x10000
	s_addc_u32 s99, s87, 0
	global_load_dwordx4 v[4:7], v180, s[98:99]
	s_waitcnt lgkmcnt(5)
	v_mfma_f32_16x16x32_bf16 v[76:79], v[216:219], v[248:251], v[76:79]
	s_waitcnt lgkmcnt(4)
	v_mfma_f32_16x16x32_bf16 v[60:63], v[216:219], v[252:255], v[60:63]
	ds_read_b128 v[216:219], v243 offset:32768
	v_mfma_f32_16x16x32_bf16 v[72:75], v[220:223], v[248:251], v[72:75]
	v_mfma_f32_16x16x32_bf16 v[56:59], v[220:223], v[252:255], v[56:59]
	ds_read_b128 v[220:223], v243 offset:34816
	v_mfma_f32_16x16x32_bf16 v[68:71], v[224:227], v[248:251], v[68:71]
	v_mfma_f32_16x16x32_bf16 v[52:55], v[224:227], v[252:255], v[52:55]
	ds_read_b128 v[224:227], v243 offset:36864
	v_mfma_f32_16x16x32_bf16 v[64:67], v[228:231], v[248:251], v[64:67]
	v_mfma_f32_16x16x32_bf16 v[48:51], v[228:231], v[252:255], v[48:51]
	ds_read_b128 v[228:231], v243 offset:38912
	ds_read_b128 v[248:251], v242 offset:12288
	ds_read_b128 v[252:255], v242 offset:14336
	s_waitcnt vmcnt(11)
	ds_write_b128 v214, v[16:19] offset:16384
	s_add_u32 s98, s86, 0x40000
	s_addc_u32 s99, s87, 0
	global_load_dwordx4 v[16:19], v180, s[98:99]
	s_waitcnt lgkmcnt(6)
	v_mfma_f32_16x16x32_bf16 v[108:111], v[216:219], v[232:235], v[108:111]
	v_mfma_f32_16x16x32_bf16 v[92:95], v[216:219], v[244:247], v[92:95]
	s_waitcnt lgkmcnt(5)
	v_mfma_f32_16x16x32_bf16 v[104:107], v[220:223], v[232:235], v[104:107]
	v_mfma_f32_16x16x32_bf16 v[88:91], v[220:223], v[244:247], v[88:91]
	s_waitcnt vmcnt(11)
	ds_write_b128 v214, v[20:23] offset:20480
	s_add_u32 s98, s86, 0x50000
	s_addc_u32 s99, s87, 0
	global_load_dwordx4 v[20:23], v180, s[98:99]
	s_waitcnt lgkmcnt(5)
	v_mfma_f32_16x16x32_bf16 v[100:103], v[224:227], v[232:235], v[100:103]
	v_mfma_f32_16x16x32_bf16 v[84:87], v[224:227], v[244:247], v[84:87]
	s_waitcnt lgkmcnt(4)
	v_mfma_f32_16x16x32_bf16 v[96:99], v[228:231], v[232:235], v[96:99]
	v_mfma_f32_16x16x32_bf16 v[80:83], v[228:231], v[244:247], v[80:83]
	s_waitcnt vmcnt(11)
	ds_write_b128 v215, v[40:43] offset:40960
	s_add_u32 s98, s34, 0x20000
	s_addc_u32 s99, s35, 0
	global_load_dwordx4 v[40:43], v180, s[98:99]
	s_waitcnt lgkmcnt(4)
	v_mfma_f32_16x16x32_bf16 v[76:79], v[216:219], v[248:251], v[76:79]
	v_mfma_f32_16x16x32_bf16 v[72:75], v[220:223], v[248:251], v[72:75]
	v_mfma_f32_16x16x32_bf16 v[68:71], v[224:227], v[248:251], v[68:71]
	v_mfma_f32_16x16x32_bf16 v[64:67], v[228:231], v[248:251], v[64:67]
	s_waitcnt vmcnt(11)
	ds_write_b128 v215, v[44:47] offset:45056
	s_add_u32 s98, s34, 0x30000
	s_addc_u32 s99, s35, 0
	global_load_dwordx4 v[44:47], v180, s[98:99]
	s_waitcnt lgkmcnt(0)
	s_barrier
	v_mfma_f32_16x16x32_bf16 v[60:63], v[216:219], v[252:255], v[60:63]
	v_mfma_f32_16x16x32_bf16 v[56:59], v[220:223], v[252:255], v[56:59]
	v_mfma_f32_16x16x32_bf16 v[52:55], v[224:227], v[252:255], v[52:55]
	v_mfma_f32_16x16x32_bf16 v[48:51], v[228:231], v[252:255], v[48:51]
	v_xor_b32_e32 v176, 0x4000, v176
	v_xor_b32_e32 v243, 0x4000, v243
	v_xor_b32_e32 v215, 0x4000, v215
	s_and_b32 s98, s28, s92
	s_cmp_lg_u32 s98, s28
	s_cbranch_scc0 .Ls_nodrain_ff1
	s_waitcnt vmcnt(0)
.Ls_nodrain_ff1:
	s_add_i32 s33, s33, 64
	s_andn2_b64 vcc, exec, s[28:29]
	s_mov_b32 s85, 0x800000
	s_cbranch_vccz .LBB0_36
	s_branch .LBB0_41

.LBB0_56:
	s_andn2_b64 vcc, exec, s[24:25]
	s_cbranch_vccnz .LBB0_138
	v_readlane_b32 s0, v236, 47
	s_cmp_lt_i32 s0, 6
	s_mov_b64 s[24:25], -1
	s_cbranch_scc1 .LBB0_105
	v_readlane_b32 s0, v236, 47
	s_cmp_gt_i32 s0, 6
	s_cbranch_scc0 .LBB0_75
	s_waitcnt lgkmcnt(2)
	v_mov_b32_e32 v48, v184
	s_mov_b32 s24, s87
	s_and_b32 s25, s24, 7
	v_readlane_b32 s0, v236, 16
	s_mul_i32 s25, s25, s0
	s_ashr_i32 s24, s24, 3
	s_add_i32 s28, s25, s24
	s_mov_b32 s84, 0x30000
	s_mov_b32 s33, 0x20000
	s_cmp_ge_i32 s28, s18
	s_cbranch_scc1 .LBB0_74
	v_readlane_b32 s0, v236, 37
	v_readlane_b32 s1, v236, 38
	s_cmp_eq_u32 s0, 0
	v_readlane_b32 s52, v240, 18
	v_readlane_b32 s0, v239, 18
	v_readlane_b32 s53, v240, 19
	v_readlane_b32 s4, v239, 22
	v_readlane_b32 s5, v239, 23
	s_cselect_b32 s25, s53, s5
	s_cselect_b32 s24, s52, s4
	s_lshl_b64 s[34:35], s[40:41], 2
	s_add_u32 s24, s24, s34
	s_addc_u32 s25, s25, s35
	s_add_u32 s36, s4, s34
	s_addc_u32 s37, s5, s35
	s_ashr_i32 s26, s28, 31
	s_lshr_b32 s26, s26, 26
	s_add_i32 s26, s28, s26
	s_ashr_i32 s29, s26, 6
	s_andn2_b32 s26, s26, 63
	s_sub_i32 s26, s28, s26
	s_lshl_b32 s29, s29, 3
	s_ashr_i32 s34, s26, 3
	s_and_b32 s26, s28, 7
	v_readlane_b32 s1, v239, 19
	v_readlane_b32 s2, v239, 20
	v_readlane_b32 s3, v239, 21
	v_readlane_b32 s6, v239, 24
	v_readlane_b32 s7, v239, 25
	v_readlane_b32 s8, v239, 26
	v_readlane_b32 s9, v239, 27
	v_readlane_b32 s10, v239, 28
	v_readlane_b32 s11, v239, 29
	v_readlane_b32 s12, v239, 30
	v_readlane_b32 s13, v239, 31
	v_readlane_b32 s14, v239, 32
	v_readlane_b32 s15, v239, 33
	s_or_b32 s38, s29, s26
	s_ashr_i32 s39, s38, 31
	v_readlane_b32 s0, v237, 30
	s_waitcnt vmcnt(17)
	v_mov_b32_e32 v4, v184
	s_lshl_b64 s[38:39], s[38:39], 19
	v_readlane_b32 s10, v237, 40
	v_readlane_b32 s11, v237, 41
	v_ashrrev_i32_e32 v0, 3, v4
	s_add_u32 s38, s10, s38
	v_ashrrev_i32_e32 v1, 31, v0
	s_addc_u32 s39, s11, s39
	v_lshlrev_b64 v[0:1], 11, v[0:1]
	v_lshlrev_b32_e32 v4, 4, v4
	v_readlane_b32 s1, v237, 31
	v_lshl_add_u64 v[2:3], s[38:39], 0, v[0:1]
	v_and_b32_e32 v176, 0x70, v4
	s_mov_b32 s1, 0x10000
	s_waitcnt vmcnt(16)
	v_lshl_add_u64 v[28:29], v[2:3], 0, v[176:177]
	v_add_co_u32_e32 v4, vcc, s1, v28
	s_mov_b32 s0, 0x40000
	s_nop 0
	v_addc_co_u32_e32 v5, vcc, 0, v29, vcc
	v_add_co_u32_e32 v8, vcc, s33, v28
	v_readlane_b32 s54, v240, 20
	s_nop 0
	v_addc_co_u32_e32 v9, vcc, 0, v29, vcc
	v_add_co_u32_e32 v12, vcc, s84, v28
	v_readlane_b32 s55, v240, 21
	s_nop 0
	v_addc_co_u32_e32 v13, vcc, 0, v29, vcc
	s_waitcnt lgkmcnt(0)
	v_add_co_u32_e32 v16, vcc, s0, v28
	s_ashr_i32 s35, s34, 31
	v_readlane_b32 s40, v239, 34
	v_addc_co_u32_e32 v17, vcc, 0, v29, vcc
	s_mov_b32 s0, 0x50000
	s_lshl_b64 s[34:35], s[34:35], 18
	v_readlane_b32 s46, v239, 40
	v_add_co_u32_e32 v20, vcc, s0, v28
	v_readlane_b32 s47, v239, 41
	s_add_u32 s34, s46, s34
	v_addc_co_u32_e32 v21, vcc, 0, v29, vcc
	s_addc_u32 s35, s47, s35
	v_add_co_u32_e32 v24, vcc, 0x60000, v28
	v_lshl_add_u64 v[0:1], s[34:35], 0, v[0:1]
	s_nop 0
	v_addc_co_u32_e32 v25, vcc, 0, v29, vcc
	s_waitcnt vmcnt(32)
	v_lshl_add_u64 v[44:45], v[0:1], 0, v[176:177]
	s_mov_b32 s100, 1
	global_load_dwordx4 v[0:3], v[28:29], off
	v_add_co_u32_e32 v28, vcc, 0x70000, v28
	global_load_dwordx4 v[4:7], v[4:5], off
	s_nop 0
	global_load_dwordx4 v[8:11], v[8:9], off
	v_addc_co_u32_e32 v29, vcc, 0, v29, vcc
	v_add_co_u32_e32 v36, vcc, s1, v44
	global_load_dwordx4 v[12:15], v[12:13], off
	s_nop 0
	global_load_dwordx4 v[16:19], v[16:17], off
	v_addc_co_u32_e32 v37, vcc, 0, v45, vcc
	v_add_co_u32_e32 v40, vcc, 0x20000, v44
	global_load_dwordx4 v[20:23], v[20:21], off
	s_nop 0
	global_load_dwordx4 v[24:27], v[24:25], off
	v_addc_co_u32_e32 v41, vcc, 0, v45, vcc
	global_load_dwordx4 v[28:31], v[28:29], off
	s_nop 0
	global_load_dwordx4 v[32:35], v[44:45], off
	v_add_co_u32_e32 v44, vcc, 0x30000, v44
	global_load_dwordx4 v[36:39], v[36:37], off
	s_nop 0
	global_load_dwordx4 v[40:43], v[40:41], off
	v_addc_co_u32_e32 v45, vcc, 0, v45, vcc
	global_load_dwordx4 v[44:47], v[44:45], off
	s_waitcnt vmcnt(27)
	v_lshrrev_b32_e32 v49, 2, v48
	v_and_b32_e32 v49, 12, v49
	v_and_b32_e32 v179, 0xffffff8f, v48
	v_and_or_b32 v213, v48, 64, v49
	v_readlane_b32 s56, v240, 22
	v_readlane_b32 s57, v240, 23
	v_readlane_b32 s58, v240, 24
	v_readlane_b32 s59, v240, 25
	v_readlane_b32 s60, v240, 26
	v_readlane_b32 s61, v240, 27
	v_readlane_b32 s62, v240, 28
	v_readlane_b32 s63, v240, 29
	v_readlane_b32 s64, v240, 30
	v_readlane_b32 s65, v240, 31
	v_readlane_b32 s66, v240, 32
	v_readlane_b32 s67, v240, 33
	v_readlane_b32 s2, v237, 32
	v_readlane_b32 s3, v237, 33
	v_readlane_b32 s4, v237, 34
	v_readlane_b32 s5, v237, 35
	v_readlane_b32 s6, v237, 36
	v_readlane_b32 s7, v237, 37
	v_readlane_b32 s8, v237, 38
	v_readlane_b32 s9, v237, 39
	v_readlane_b32 s12, v237, 42
	v_readlane_b32 s13, v237, 43
	v_readlane_b32 s14, v237, 44
	v_readlane_b32 s15, v237, 45
	v_readlane_b32 s41, v239, 35
	v_readlane_b32 s42, v239, 36
	v_readlane_b32 s43, v239, 37
	v_readlane_b32 s44, v239, 38
	v_readlane_b32 s45, v239, 39
	v_readlane_b32 s48, v239, 42
	v_readlane_b32 s49, v239, 43
	v_readlane_b32 s50, v239, 44
	v_readlane_b32 s51, v239, 45
	v_readlane_b32 s52, v239, 46
	v_readlane_b32 s53, v239, 47
	v_readlane_b32 s54, v239, 48
	v_readlane_b32 s55, v239, 49
	s_branch .LBB0_62

.LBB0_66:
	s_cmpk_gt_u32 s33, 0x3bf
	s_cselect_b64 s[28:29], -1, 0
	s_cmp_lg_u32 s33, 0
	s_cbranch_scc1 .Ls_nosetup_wout
	v_add_u32_e32 v176, v182, v180
	v_add_u32_e32 v243, v182, v183
	v_add_u32_e32 v241, v181, v180
	v_add_u32_e32 v242, v181, v183
	v_or_b32_e32 v215, 0x4000, v214
	v_lshrrev_b32_e32 v180, 3, v184
	v_and_b32_e32 v181, 7, v184
	v_lshlrev_b32_e32 v180, 11, v180
	v_lshl_add_u32 v180, v181, 4, v180
	s_cmp_eq_u32 s100, 0
	s_cbranch_scc1 .Ls_nosetup_wout
	s_mov_b32 s100, 0
	s_waitcnt vmcnt(0)
	ds_write_b128 v214, v[0:3]
	ds_write_b128 v214, v[4:7] offset:4096
	ds_write_b128 v214, v[16:19] offset:16384
	ds_write_b128 v214, v[20:23] offset:20480
	ds_write_b128 v214, v[32:35] offset:32768
	ds_write_b128 v214, v[36:39] offset:36864
	ds_write_b128 v214, v[40:43] offset:40960
	ds_write_b128 v214, v[44:47] offset:45056
	s_add_u32 s86, s50, 128
	s_addc_u32 s87, s51, 0
	s_add_u32 s34, s92, 128
	s_addc_u32 s35, s93, 0
	global_load_dwordx4 v[32:35], v180, s[34:35]
	s_add_u32 s98, s34, 0x10000
	s_addc_u32 s99, s35, 0
	global_load_dwordx4 v[36:39], v180, s[98:99]
	global_load_dwordx4 v[0:3], v180, s[86:87]
	s_add_u32 s98, s86, 0x10000
	s_addc_u32 s99, s87, 0
	global_load_dwordx4 v[4:7], v180, s[98:99]
	s_add_u32 s98, s86, 0x40000
	s_addc_u32 s99, s87, 0
	global_load_dwordx4 v[16:19], v180, s[98:99]
	s_add_u32 s98, s86, 0x50000
	s_addc_u32 s99, s87, 0
	global_load_dwordx4 v[20:23], v180, s[98:99]
	s_add_u32 s98, s34, 0x20000
	s_addc_u32 s99, s35, 0
	global_load_dwordx4 v[40:43], v180, s[98:99]
	s_add_u32 s98, s34, 0x30000
	s_addc_u32 s99, s35, 0
	global_load_dwordx4 v[44:47], v180, s[98:99]
	s_waitcnt lgkmcnt(0)
	s_barrier
.Ls_nosetup_wout:
	s_add_i32 s101, s33, 64
	s_cmpk_ge_u32 s101, 0x400
	s_cselect_b32 s98, 0x400, 0
	s_cselect_b32 s99, s94, 0
	s_sub_u32 s101, s101, s98
	s_lshl_b32 s101, s101, 1
	s_cmp_lg_u32 s99, 0
	s_cselect_b64 s[84:85], s[40:41], s[50:51]
	s_add_u32 s84, s84, s101
	s_addc_u32 s85, s85, 0
	s_add_i32 s101, s33, 128
	s_cmpk_ge_u32 s101, 0x400
	s_cselect_b32 s98, 0x400, 0
	s_cselect_b32 s99, s94, 0
	s_sub_u32 s101, s101, s98
	s_lshl_b32 s101, s101, 1
	s_cmp_lg_u32 s99, 0
	s_cselect_b64 s[86:87], s[40:41], s[50:51]
	s_cselect_b64 s[34:35], s[42:43], s[92:93]
	s_add_u32 s86, s86, s101
	s_addc_u32 s87, s87, 0
	s_add_u32 s34, s34, s101
	s_addc_u32 s35, s35, 0
	ds_read_b128 v[216:219], v176 offset:32768
	ds_read_b128 v[232:235], v241
	ds_read_b128 v[220:223], v176 offset:34816
	ds_read_b128 v[224:227], v176 offset:36864
	ds_read_b128 v[228:231], v176 offset:38912
	ds_read_b128 v[244:247], v241 offset:2048
	ds_read_b128 v[248:251], v241 offset:4096
	ds_read_b128 v[252:255], v241 offset:6144
	s_waitcnt lgkmcnt(6)
	v_mfma_f32_16x16x32_bf16 v[172:175], v[216:219], v[232:235], v[172:175]
	s_waitcnt lgkmcnt(5)
	v_mfma_f32_16x16x32_bf16 v[168:171], v[220:223], v[232:235], v[168:171]
	s_waitcnt lgkmcnt(4)
	v_mfma_f32_16x16x32_bf16 v[164:167], v[224:227], v[232:235], v[164:167]
	s_waitcnt lgkmcnt(3)
	v_mfma_f32_16x16x32_bf16 v[160:163], v[228:231], v[232:235], v[160:163]
	ds_read_b128 v[232:235], v242
	s_waitcnt vmcnt(11)
	ds_write_b128 v214, v[8:11] offset:8192
	s_add_u32 s98, s84, 0x20000
	s_addc_u32 s99, s85, 0
	global_load_dwordx4 v[8:11], v180, s[98:99]
	s_waitcnt lgkmcnt(4)
	v_mfma_f32_16x16x32_bf16 v[156:159], v[216:219], v[244:247], v[156:159]
	v_mfma_f32_16x16x32_bf16 v[152:155], v[220:223], v[244:247], v[152:155]
	v_mfma_f32_16x16x32_bf16 v[148:151], v[224:227], v[244:247], v[148:151]
	v_mfma_f32_16x16x32_bf16 v[144:147], v[228:231], v[244:247], v[144:147]
	ds_read_b128 v[244:247], v242 offset:2048
	s_waitcnt vmcnt(11)
	ds_write_b128 v214, v[12:15] offset:12288
	s_add_u32 s98, s84, 0x30000
	s_addc_u32 s99, s85, 0
	global_load_dwordx4 v[12:15], v180, s[98:99]
	s_waitcnt lgkmcnt(5)
	v_mfma_f32_16x16x32_bf16 v[140:143], v[216:219], v[248:251], v[140:143]
	s_waitcnt lgkmcnt(4)
	v_mfma_f32_16x16x32_bf16 v[124:127], v[216:219], v[252:255], v[124:127]
	ds_read_b128 v[216:219], v243 offset:32768
	v_mfma_f32_16x16x32_bf16 v[136:139], v[220:223], v[248:251], v[136:139]
	v_mfma_f32_16x16x32_bf16 v[120:123], v[220:223], v[252:255], v[120:123]
	ds_read_b128 v[220:223], v243 offset:34816
	v_mfma_f32_16x16x32_bf16 v[132:135], v[224:227], v[248:251], v[132:135]
	v_mfma_f32_16x16x32_bf16 v[116:119], v[224:227], v[252:255], v[116:119]
	ds_read_b128 v[224:227], v243 offset:36864
	v_mfma_f32_16x16x32_bf16 v[128:131], v[228:231], v[248:251], v[128:131]
	v_mfma_f32_16x16x32_bf16 v[112:115], v[228:231], v[252:255], v[112:115]
	ds_read_b128 v[228:231], v243 offset:38912
	ds_read_b128 v[248:251], v242 offset:4096
	ds_read_b128 v[252:255], v242 offset:6144
	s_waitcnt vmcnt(11)
	ds_write_b128 v214, v[24:27] offset:24576
	s_add_u32 s98, s84, 0x60000
	s_addc_u32 s99, s85, 0
	global_load_dwordx4 v[24:27], v180, s[98:99]
	s_waitcnt lgkmcnt(6)
	v_mfma_f32_16x16x32_bf16 v[172:175], v[216:219], v[232:235], v[172:175]
	v_mfma_f32_16x16x32_bf16 v[156:159], v[216:219], v[244:247], v[156:159]
	s_waitcnt lgkmcnt(5)
	v_mfma_f32_16x16x32_bf16 v[168:171], v[220:223], v[232:235], v[168:171]
	v_mfma_f32_16x16x32_bf16 v[152:155], v[220:223], v[244:247], v[152:155]
	s_waitcnt vmcnt(11)
	ds_write_b128 v214, v[28:31] offset:28672
	s_add_u32 s98, s84, 0x70000
	s_addc_u32 s99, s85, 0
	global_load_dwordx4 v[28:31], v180, s[98:99]
	s_waitcnt lgkmcnt(5)
	v_mfma_f32_16x16x32_bf16 v[164:167], v[224:227], v[232:235], v[164:167]
	v_mfma_f32_16x16x32_bf16 v[148:151], v[224:227], v[244:247], v[148:151]
	s_waitcnt lgkmcnt(4)
	v_mfma_f32_16x16x32_bf16 v[160:163], v[228:231], v[232:235], v[160:163]
	v_mfma_f32_16x16x32_bf16 v[144:147], v[228:231], v[244:247], v[144:147]
	s_waitcnt vmcnt(11)
	ds_write_b128 v215, v[32:35] offset:32768
	global_load_dwordx4 v[32:35], v180, s[34:35]
	s_waitcnt lgkmcnt(4)
	v_mfma_f32_16x16x32_bf16 v[140:143], v[216:219], v[248:251], v[140:143]
	v_mfma_f32_16x16x32_bf16 v[136:139], v[220:223], v[248:251], v[136:139]
	v_mfma_f32_16x16x32_bf16 v[132:135], v[224:227], v[248:251], v[132:135]
	v_mfma_f32_16x16x32_bf16 v[128:131], v[228:231], v[248:251], v[128:131]
	s_waitcnt vmcnt(11)
	ds_write_b128 v215, v[36:39] offset:36864
	s_add_u32 s98, s34, 0x10000
	s_addc_u32 s99, s35, 0
	global_load_dwordx4 v[36:39], v180, s[98:99]
	s_waitcnt lgkmcnt(0)
	s_barrier
	v_mfma_f32_16x16x32_bf16 v[124:127], v[216:219], v[252:255], v[124:127]
	v_mfma_f32_16x16x32_bf16 v[120:123], v[220:223], v[252:255], v[120:123]
	v_mfma_f32_16x16x32_bf16 v[116:119], v[224:227], v[252:255], v[116:119]
	v_mfma_f32_16x16x32_bf16 v[112:115], v[228:231], v[252:255], v[112:115]
	ds_read_b128 v[216:219], v176 offset:32768
	ds_read_b128 v[232:235], v241 offset:8192
	ds_read_b128 v[220:223], v176 offset:34816
	ds_read_b128 v[224:227], v176 offset:36864
	ds_read_b128 v[228:231], v176 offset:38912
	ds_read_b128 v[244:247], v241 offset:10240
	ds_read_b128 v[248:251], v241 offset:12288
	ds_read_b128 v[252:255], v241 offset:14336
	s_waitcnt lgkmcnt(6)
	v_mfma_f32_16x16x32_bf16 v[108:111], v[216:219], v[232:235], v[108:111]
	s_waitcnt lgkmcnt(5)
	v_mfma_f32_16x16x32_bf16 v[104:107], v[220:223], v[232:235], v[104:107]
	s_waitcnt lgkmcnt(4)
	v_mfma_f32_16x16x32_bf16 v[100:103], v[224:227], v[232:235], v[100:103]
	s_waitcnt lgkmcnt(3)
	v_mfma_f32_16x16x32_bf16 v[96:99], v[228:231], v[232:235], v[96:99]
	ds_read_b128 v[232:235], v242 offset:8192
	s_waitcnt vmcnt(11)
	ds_write_b128 v214, v[0:3]
	global_load_dwordx4 v[0:3], v180, s[86:87]
	s_waitcnt lgkmcnt(4)
	v_mfma_f32_16x16x32_bf16 v[92:95], v[216:219], v[244:247], v[92:95]
	v_mfma_f32_16x16x32_bf16 v[88:91], v[220:223], v[244:247], v[88:91]
	v_mfma_f32_16x16x32_bf16 v[84:87], v[224:227], v[244:247], v[84:87]
	v_mfma_f32_16x16x32_bf16 v[80:83], v[228:231], v[244:247], v[80:83]
	ds_read_b128 v[244:247], v242 offset:10240
	s_waitcnt vmcnt(11)
	ds_write_b128 v214, v[4:7] offset:4096
	s_add_u32 s98, s86, 0x10000
	s_addc_u32 s99, s87, 0
	global_load_dwordx4 v[4:7], v180, s[98:99]
	s_waitcnt lgkmcnt(5)
	v_mfma_f32_16x16x32_bf16 v[76:79], v[216:219], v[248:251], v[76:79]
	s_waitcnt lgkmcnt(4)
	v_mfma_f32_16x16x32_bf16 v[60:63], v[216:219], v[252:255], v[60:63]
	ds_read_b128 v[216:219], v243 offset:32768
	v_mfma_f32_16x16x32_bf16 v[72:75], v[220:223], v[248:251], v[72:75]
	v_mfma_f32_16x16x32_bf16 v[56:59], v[220:223], v[252:255], v[56:59]
	ds_read_b128 v[220:223], v243 offset:34816
	v_mfma_f32_16x16x32_bf16 v[68:71], v[224:227], v[248:251], v[68:71]
	v_mfma_f32_16x16x32_bf16 v[52:55], v[224:227], v[252:255], v[52:55]
	ds_read_b128 v[224:227], v243 offset:36864
	v_mfma_f32_16x16x32_bf16 v[64:67], v[228:231], v[248:251], v[64:67]
	v_mfma_f32_16x16x32_bf16 v[48:51], v[228:231], v[252:255], v[48:51]
	ds_read_b128 v[228:231], v243 offset:38912
	ds_read_b128 v[248:251], v242 offset:12288
	ds_read_b128 v[252:255], v242 offset:14336
	s_waitcnt vmcnt(11)
	ds_write_b128 v214, v[16:19] offset:16384
	s_add_u32 s98, s86, 0x40000
	s_addc_u32 s99, s87, 0
	global_load_dwordx4 v[16:19], v180, s[98:99]
	s_waitcnt lgkmcnt(6)
	v_mfma_f32_16x16x32_bf16 v[108:111], v[216:219], v[232:235], v[108:111]
	v_mfma_f32_16x16x32_bf16 v[92:95], v[216:219], v[244:247], v[92:95]
	s_waitcnt lgkmcnt(5)
	v_mfma_f32_16x16x32_bf16 v[104:107], v[220:223], v[232:235], v[104:107]
	v_mfma_f32_16x16x32_bf16 v[88:91], v[220:223], v[244:247], v[88:91]
	s_waitcnt vmcnt(11)
	ds_write_b128 v214, v[20:23] offset:20480
	s_add_u32 s98, s86, 0x50000
	s_addc_u32 s99, s87, 0
	global_load_dwordx4 v[20:23], v180, s[98:99]
	s_waitcnt lgkmcnt(5)
	v_mfma_f32_16x16x32_bf16 v[100:103], v[224:227], v[232:235], v[100:103]
	v_mfma_f32_16x16x32_bf16 v[84:87], v[224:227], v[244:247], v[84:87]
	s_waitcnt lgkmcnt(4)
	v_mfma_f32_16x16x32_bf16 v[96:99], v[228:231], v[232:235], v[96:99]
	v_mfma_f32_16x16x32_bf16 v[80:83], v[228:231], v[244:247], v[80:83]
	s_waitcnt vmcnt(11)
	ds_write_b128 v215, v[40:43] offset:40960
	s_add_u32 s98, s34, 0x20000
	s_addc_u32 s99, s35, 0
	global_load_dwordx4 v[40:43], v180, s[98:99]
	s_waitcnt lgkmcnt(4)
	v_mfma_f32_16x16x32_bf16 v[76:79], v[216:219], v[248:251], v[76:79]
	v_mfma_f32_16x16x32_bf16 v[72:75], v[220:223], v[248:251], v[72:75]
	v_mfma_f32_16x16x32_bf16 v[68:71], v[224:227], v[248:251], v[68:71]
	v_mfma_f32_16x16x32_bf16 v[64:67], v[228:231], v[248:251], v[64:67]
	s_waitcnt vmcnt(11)
	ds_write_b128 v215, v[44:47] offset:45056
	s_add_u32 s98, s34, 0x30000
	s_addc_u32 s99, s35, 0
	global_load_dwordx4 v[44:47], v180, s[98:99]
	s_waitcnt lgkmcnt(0)
	s_barrier
	v_mfma_f32_16x16x32_bf16 v[60:63], v[216:219], v[252:255], v[60:63]
	v_mfma_f32_16x16x32_bf16 v[56:59], v[220:223], v[252:255], v[56:59]
	v_mfma_f32_16x16x32_bf16 v[52:55], v[224:227], v[252:255], v[52:55]
	v_mfma_f32_16x16x32_bf16 v[48:51], v[228:231], v[252:255], v[48:51]
	v_xor_b32_e32 v176, 0x4000, v176
	v_xor_b32_e32 v243, 0x4000, v243
	v_xor_b32_e32 v215, 0x4000, v215
	s_and_b32 s98, s28, s94
	s_cmp_lg_u32 s98, s28
	s_cbranch_scc0 .Ls_nodrain_wout
	s_waitcnt vmcnt(0)

.LBB0_650:
	s_cmpk_gt_u32 s25, 0x3bf
	s_cselect_b64 s[28:29], -1, 0
	v_lshrrev_b32_e32 v216, 3, v184
	v_and_b32_e32 v217, 7, v184
	v_lshlrev_b32_e32 v216, 11, v216
	v_lshl_add_u32 v216, v217, 4, v216
	s_cbranch_scc1 .Lw_last_0
	s_add_i32 s98, s25, 64
	s_lshl_b32 s98, s98, 1
	v_add_u32_e32 v216, s98, v216
	v_add_u32_e32 v217, 0x10000, v216
	v_add_u32_e32 v218, 0x20000, v216
	v_add_u32_e32 v219, 0x30000, v216
	v_add_u32_e32 v220, 0x40000, v216
	v_add_u32_e32 v221, 0x50000, v216
	v_add_u32_e32 v222, 0x60000, v216
	v_add_u32_e32 v223, 0x70000, v216
	s_waitcnt vmcnt(11)
	ds_write_b128 v214, v[68:71]
	global_load_dwordx4 v[68:71], v216, s[40:41]
	s_waitcnt vmcnt(11)
	ds_write_b128 v214, v[76:79] offset:4096
	global_load_dwordx4 v[76:79], v217, s[40:41]
	s_waitcnt vmcnt(11)
	ds_write_b128 v214, v[84:87] offset:8192
	global_load_dwordx4 v[84:87], v218, s[40:41]
	s_waitcnt vmcnt(11)
	ds_write_b128 v214, v[92:95] offset:12288
	global_load_dwordx4 v[92:95], v219, s[40:41]
	s_waitcnt vmcnt(11)
	ds_write_b128 v214, v[96:99] offset:16384
	global_load_dwordx4 v[96:99], v220, s[40:41]
	s_waitcnt vmcnt(11)
	ds_write_b128 v214, v[104:107] offset:20480
	global_load_dwordx4 v[104:107], v221, s[40:41]
	s_waitcnt vmcnt(11)
	ds_write_b128 v214, v[108:111] offset:24576
	global_load_dwordx4 v[108:111], v222, s[40:41]
	s_waitcnt vmcnt(11)
	ds_write_b128 v214, v[116:119] offset:28672
	global_load_dwordx4 v[116:119], v223, s[40:41]
	s_waitcnt vmcnt(11)
	ds_write_b128 v214, v[120:123] offset:32768
	global_load_dwordx4 v[120:123], v216, s[42:43]
	s_waitcnt vmcnt(11)
	ds_write_b128 v214, v[128:131] offset:36864
	global_load_dwordx4 v[128:131], v217, s[42:43]
	s_waitcnt vmcnt(11)
	ds_write_b128 v214, v[132:135] offset:40960
	global_load_dwordx4 v[132:135], v218, s[42:43]
	s_waitcnt vmcnt(11)
	ds_write_b128 v214, v[140:143] offset:45056
	global_load_dwordx4 v[140:143], v219, s[42:43]
	s_branch .Lw_done_0
.Lw_last_0:
	s_waitcnt vmcnt(11)
	ds_write_b128 v214, v[68:71]
	s_waitcnt vmcnt(10)
	ds_write_b128 v214, v[76:79] offset:4096
	s_waitcnt vmcnt(9)
	ds_write_b128 v214, v[84:87] offset:8192
	s_waitcnt vmcnt(8)
	ds_write_b128 v214, v[92:95] offset:12288
	s_waitcnt vmcnt(7)
	ds_write_b128 v214, v[96:99] offset:16384
	s_waitcnt vmcnt(6)
	ds_write_b128 v214, v[104:107] offset:20480
	s_waitcnt vmcnt(5)
	ds_write_b128 v214, v[108:111] offset:24576
	s_waitcnt vmcnt(4)
	ds_write_b128 v214, v[116:119] offset:28672
	s_waitcnt vmcnt(3)
	ds_write_b128 v214, v[120:123] offset:32768
	s_waitcnt vmcnt(2)
	ds_write_b128 v214, v[128:131] offset:36864
	s_waitcnt vmcnt(1)
	ds_write_b128 v214, v[132:135] offset:40960
	s_waitcnt vmcnt(0)
	ds_write_b128 v214, v[140:143] offset:45056
.Lw_done_0:
	s_waitcnt lgkmcnt(0)
	s_barrier
	s_branch .LBB0_649

	.amdhsa_kernel _Z4mega6Paramsii
		.amdhsa_group_segment_fixed_size 66560
		.amdhsa_private_segment_fixed_size 0
		.amdhsa_kernarg_size 952
		.amdhsa_user_sgpr_count 2
		.amdhsa_user_sgpr_dispatch_ptr 0
		.amdhsa_user_sgpr_queue_ptr 0
		.amdhsa_user_sgpr_kernarg_segment_ptr 1
		.amdhsa_user_sgpr_dispatch_id 0
		.amdhsa_user_sgpr_kernarg_preload_length 0
		.amdhsa_user_sgpr_kernarg_preload_offset 0
		.amdhsa_user_sgpr_private_segment_size 0
		.amdhsa_uses_dynamic_stack 0
		.amdhsa_enable_private_segment 0
		.amdhsa_system_sgpr_workgroup_id_x 1
		.amdhsa_system_sgpr_workgroup_id_y 0
		.amdhsa_system_sgpr_workgroup_id_z 0
		.amdhsa_system_sgpr_workgroup_info 0
		.amdhsa_system_vgpr_workitem_id 2
		.amdhsa_next_free_vgpr 256
		.amdhsa_next_free_sgpr 102
		.amdhsa_accum_offset 256
		.amdhsa_reserve_vcc 1
		.amdhsa_float_round_mode_32 0
		.amdhsa_float_round_mode_16_64 0
		.amdhsa_float_denorm_mode_32 3
		.amdhsa_float_denorm_mode_16_64 3
		.amdhsa_dx10_clamp 1
		.amdhsa_ieee_mode 1
		.amdhsa_fp16_overflow 0
		.amdhsa_tg_split 0
		.amdhsa_exception_fp_ieee_invalid_op 0
		.amdhsa_exception_fp_denorm_src 0
		.amdhsa_exception_fp_ieee_div_zero 0
		.amdhsa_exception_fp_ieee_overflow 0
		.amdhsa_exception_fp_ieee_underflow 0
		.amdhsa_exception_fp_ieee_inexact 0
		.amdhsa_exception_int_div_zero 0
	.end_amdhsa_kernel

amdhsa.kernels:
  - .agpr_count:     0
    .args:
      - .offset:         0
        .size:           688
        .value_kind:     by_value
      - .offset:         688
        .size:           4
        .value_kind:     by_value
      - .offset:         692
        .size:           4
        .value_kind:     by_value
      - .offset:         696
        .size:           4
        .value_kind:     hidden_block_count_x
      - .offset:         700
        .size:           4
        .value_kind:     hidden_block_count_y
      - .offset:         704
        .size:           4
        .value_kind:     hidden_block_count_z
      - .offset:         708
        .size:           2
        .value_kind:     hidden_group_size_x
      - .offset:         710
        .size:           2
        .value_kind:     hidden_group_size_y
      - .offset:         712
        .size:           2
        .value_kind:     hidden_group_size_z
      - .offset:         714
        .size:           2
        .value_kind:     hidden_remainder_x
      - .offset:         716
        .size:           2
        .value_kind:     hidden_remainder_y
      - .offset:         718
        .size:           2
        .value_kind:     hidden_remainder_z
      - .offset:         736
        .size:           8
        .value_kind:     hidden_global_offset_x
      - .offset:         744
        .size:           8
        .value_kind:     hidden_global_offset_y
      - .offset:         752
        .size:           8
        .value_kind:     hidden_global_offset_z
      - .offset:         760
        .size:           2
        .value_kind:     hidden_grid_dims
      - .offset:         784
        .size:           8
        .value_kind:     hidden_multigrid_sync_arg
    .group_segment_fixed_size: 66560
    .kernarg_segment_align: 8
    .kernarg_segment_size: 952
    .language:       OpenCL C
    .language_version:
      - 2
      - 0
    .max_flat_workgroup_size: 256
    .name:           _Z4mega6Paramsii
    .private_segment_fixed_size: 0
    .sgpr_count:     108
    .sgpr_spill_count: 311
    .symbol:         _Z4mega6Paramsii.kd
    .uniform_work_group_size: 1
    .uses_dynamic_stack: false
    .vgpr_count:     256
    .vgpr_spill_count: 0
    .wavefront_size: 64
